# RNN y stores written through (sc1): the mixer's last stores no longer sit dirty in L2 at the grid barrier
# speedup vs baseline: 1.0074x; 1.0074x over previous
.LBB0_84:
	s_waitcnt lgkmcnt(0)
	s_barrier
	v_add_u32_e32 v0, v171, v228
	ds_read_u16 v2, v0
	ds_read_u16 v3, v0 offset:272
	v_lshlrev_b64 v[6:7], 12, v[168:169]
	v_lshl_add_u64 v[6:7], s[0:1], 0, v[6:7]
	v_mov_b32_e32 v171, v1
	v_lshl_add_u64 v[6:7], v[6:7], 0, v[170:171]
	s_waitcnt lgkmcnt(0)
	v_lshl_or_b32 v2, v3, 16, v2
	ds_read_u16 v3, v0 offset:544
	ds_read_u16 v4, v0 offset:816
	s_mov_b32 s0, 0xf80000
	v_add_co_u32_e32 v6, vcc, s0, v6
	v_readlane_b32 s0, v253, 1
	s_waitcnt lgkmcnt(0)
	v_lshl_or_b32 v3, v4, 16, v3
	ds_read_u16 v4, v0 offset:1088
	ds_read_u16 v5, v0 offset:1360
	v_addc_co_u32_e32 v7, vcc, 0, v7, vcc
	v_readlane_b32 s1, v253, 2
	s_waitcnt lgkmcnt(0)
	v_lshl_or_b32 v4, v5, 16, v4
	ds_read_u16 v5, v0 offset:1632
	ds_read_u16 v0, v0 offset:1904
	s_waitcnt lgkmcnt(0)
	v_lshl_or_b32 v5, v0, 16, v5
	global_store_dwordx4 v[6:7], v[2:5], off sc1
	s_waitcnt lgkmcnt(0)
	s_barrier
	s_load_dword s0, s[0:1], 0x10
	s_waitcnt lgkmcnt(0)
	s_lshr_b32 s0, s0, 16
	s_cmp_lg_u32 s0, 0
	s_cselect_b64 s[0:1], -1, 0
	s_cmp_lg_u64 s[0:1], 0
	s_addc_u32 s22, s22, s94
	s_cmpk_gt_i32 s22, 0xff
	s_cbranch_scc1 .Lmix_rnn_done

.LBB0_109:
	s_or_b64 exec, exec, s[10:11]
	s_lshl_b64 s[20:21], s[0:1], 12
	s_add_u32 s0, s16, s20
	s_addc_u32 s1, s17, s21
	s_add_u32 s0, s0, s6
	s_addc_u32 s1, s1, 0
	s_add_u32 s0, s0, s7
	v_ashrrev_i32_e32 v0, 6, v182
	s_addc_u32 s1, s1, 0
	v_mov_b32_e32 v171, v1
	v_lshlrev_b32_e32 v148, 1, v168
	v_lshl_or_b32 v142, v0, 2, v213
	v_lshl_add_u64 v[146:147], s[0:1], 0, v[170:171]
	v_lshl_add_u64 v[2:3], s[26:27], 0, v[170:171]
	v_add_u32_e32 v171, s52, v148
	v_lshlrev_b32_e32 v0, 4, v0
	s_movk_i32 s6, 0x420
	v_add3_u32 v143, v213, v141, v0
	v_or_b32_e32 v220, v0, v141
	v_lshl_add_u32 v224, v141, 6, s98
	v_mul_lo_u32 v225, v142, s6
	v_mul_lo_u32 v142, v142, s51
	v_lshlrev_b32_e32 v0, 4, v141
	v_mad_u32_u24 v141, v183, s51, v171
	v_mul_lo_u32 v150, v143, s51
	v_add_u32_e32 v226, s99, v142
	v_add_u32_e32 v227, s52, v142
	ds_read_u16 v142, v141
	ds_read_u16 v151, v141 offset:272
	ds_read_u16 v143, v141 offset:544
	ds_read_u16 v153, v141 offset:816
	ds_read_u16 v144, v141 offset:1088
	ds_read_u16 v155, v141 offset:1360
	ds_read_u16 v145, v141 offset:1632
	ds_read_u16 v141, v141 offset:1904
	v_lshlrev_b64 v[184:185], 12, v[168:169]
	v_mad_u32_u24 v152, v183, s51, v252
	s_waitcnt lgkmcnt(4)
	v_perm_b32 v143, v153, v143, s8
	s_waitcnt lgkmcnt(2)
	v_perm_b32 v144, v155, v144, s8
	s_waitcnt lgkmcnt(0)
	v_perm_b32 v145, v141, v145, s8
	v_mov_b32_e32 v141, s99
	v_mad_u32_u24 v141, v183, s51, v141
	v_perm_b32 v142, v151, v142, s8
	v_lshl_add_u64 v[146:147], v[146:147], 0, v[184:185]
	v_add_u32_e32 v175, v141, v148
	global_store_dwordx4 v[146:147], v[142:145], off sc1
	ds_write_b16 v175, v120
	ds_write_b16_d16_hi v175, v120 offset:272
	v_add_u32_e32 v120, s99, v152
	v_add_u32_e32 v200, s99, v148
	v_mad_u32_u24 v154, v183, s51, v194
	v_add_u32_e32 v141, v200, v152
	v_add_u32_e32 v201, v120, v148
	v_mad_u32_u24 v156, v183, s51, v195
	ds_write_b16 v141, v121
	ds_write_b16_d16_hi v201, v121 offset:272
	v_add_u32_e32 v120, s99, v154
	v_add_u32_e32 v121, v200, v154
	ds_write_b16 v121, v122
	v_add_u32_e32 v202, v120, v148
	v_add_u32_e32 v120, s99, v156
	v_add_u32_e32 v121, v200, v156
	v_and_b32_e32 v149, 48, v182
	ds_write_b16 v121, v123
	v_add_u32_e32 v203, v120, v148
	v_lshlrev_b64 v[120:121], 11, v[168:169]
	v_lshl_add_u64 v[120:121], v[2:3], 0, v[120:121]
	s_mov_b32 s6, 0x40000
	v_add_u32_e32 v141, 0, v149
	ds_write_b16_d16_hi v202, v122 offset:272
	ds_write_b16_d16_hi v203, v123 offset:272
	v_add_co_u32_e32 v120, vcc, s6, v120
	v_add_u32_e32 v204, 0x19c00, v141
	s_nop 0
	v_addc_co_u32_e32 v121, vcc, 0, v121, vcc
	ds_read_b128 v[142:145], v204
	global_load_dwordx4 v[120:123], v[120:121], off
	v_add_u32_e32 v205, 0, v150
	ds_read_b128 v[146:149], v204 offset:64
	ds_read_b128 v[150:153], v205
	ds_read_b128 v[154:157], v205 offset:16
	ds_read_b128 v[158:161], v205 offset:32
	ds_read_b128 v[162:165], v205 offset:48
	s_waitcnt lgkmcnt(3)
	v_mfma_f32_16x16x32_bf16 v[142:145], v[4:7], v[150:153], v[142:145]
	s_cmp_eq_u32 s28, 0
	s_cselect_b64 vcc, -1, 0
	s_cmp_eq_u32 s28, 1
	s_waitcnt lgkmcnt(1)
	v_mfma_f32_16x16x32_bf16 v[146:149], v[12:15], v[158:161], v[146:149]
	s_cselect_b64 s[40:41], -1, 0
	s_cmp_eq_u32 s28, 2
	s_cselect_b64 s[42:43], -1, 0
	v_mfma_f32_16x16x32_bf16 v[142:145], v[8:11], v[154:157], v[142:145]
	s_cmp_eq_u32 s28, 3
	s_cselect_b64 s[44:45], -1, 0
	s_add_i32 s6, 0, 0x19800
	s_waitcnt lgkmcnt(0)
	v_mfma_f32_16x16x32_bf16 v[146:149], v[16:19], v[162:165], v[146:149]
	v_add_u32_e32 v224, v224, v225
	s_nop 1
	v_cvt_pk_bf16_f32 v142, v142, v143
	v_cvt_pk_bf16_f32 v143, v144, v145
	v_cndmask_b32_e32 v167, 0, v142, vcc
	v_cndmask_b32_e32 v190, 0, v143, vcc
	s_nop 0
	v_cvt_pk_bf16_f32 v144, v146, v147
	v_cvt_pk_bf16_f32 v145, v148, v149
	v_cndmask_b32_e32 v141, 0, v144, vcc
	v_cndmask_b32_e32 v166, 0, v145, vcc
	v_mfma_f32_16x16x32_bf16 v[146:149], v[52:55], v[142:145], 0
	v_add_u32_e32 v226, v226, v0
	v_add_u32_e32 v227, v227, v0
	v_mfma_f32_16x16x32_bf16 v[150:153], v[68:71], v[142:145], 0
	v_mfma_f32_16x16x32_bf16 v[154:157], v[84:87], v[142:145], 0
	v_mfma_f32_16x16x32_bf16 v[158:161], v[100:103], v[142:145], 0
	ds_read_b128 v[142:145], v204 offset:128
	ds_read_b128 v[162:165], v205 offset:64
	ds_read_b128 v[206:209], v205 offset:80
	ds_read_b128 v[228:231], v204 offset:192
	ds_read_b128 v[238:241], v205 offset:96
	ds_read_b128 v[242:245], v205 offset:112
	s_waitcnt lgkmcnt(4)
	v_mfma_f32_16x16x32_bf16 v[142:145], v[20:23], v[162:165], v[142:145]
	s_waitcnt lgkmcnt(1)
	v_mfma_f32_16x16x32_bf16 v[162:165], v[28:31], v[238:241], v[228:231]
	v_mfma_f32_16x16x32_bf16 v[142:145], v[24:27], v[206:209], v[142:145]
	s_waitcnt lgkmcnt(0)
	v_mfma_f32_16x16x32_bf16 v[162:165], v[32:35], v[242:245], v[162:165]
	s_nop 5
	v_cvt_pk_bf16_f32 v142, v142, v143
	v_cvt_pk_bf16_f32 v143, v144, v145
	v_cvt_pk_bf16_f32 v144, v162, v163
	v_cvt_pk_bf16_f32 v145, v164, v165
	v_cndmask_b32_e64 v166, v166, v145, s[40:41]
	v_cndmask_b32_e64 v141, v141, v144, s[40:41]
	v_mfma_f32_16x16x32_bf16 v[146:149], v[56:59], v[142:145], v[146:149]
	v_cndmask_b32_e64 v190, v190, v143, s[40:41]
	v_cndmask_b32_e64 v167, v167, v142, s[40:41]
	v_mfma_f32_16x16x32_bf16 v[150:153], v[72:75], v[142:145], v[150:153]
	v_mfma_f32_16x16x32_bf16 v[154:157], v[88:91], v[142:145], v[154:157]
	v_mfma_f32_16x16x32_bf16 v[158:161], v[104:107], v[142:145], v[158:161]
	ds_read_b128 v[142:145], v204 offset:256
	ds_read_b128 v[162:165], v205 offset:128
	ds_read_b128 v[206:209], v205 offset:144
	ds_read_b128 v[228:231], v204 offset:320
	ds_read_b128 v[238:241], v205 offset:160
	ds_read_b128 v[242:245], v205 offset:176
	s_waitcnt lgkmcnt(4)
	v_mfma_f32_16x16x32_bf16 v[142:145], v[36:39], v[162:165], v[142:145]
	s_waitcnt lgkmcnt(1)
	v_mfma_f32_16x16x32_bf16 v[162:165], v[44:47], v[238:241], v[228:231]
	v_mfma_f32_16x16x32_bf16 v[142:145], v[40:43], v[206:209], v[142:145]
	v_add_u32_e32 v206, 0x21a00, v140
	v_add_u32_e32 v207, 0x22200, v140
	s_waitcnt lgkmcnt(0)
	v_mfma_f32_16x16x32_bf16 v[162:165], v[48:51], v[242:245], v[162:165]
	s_nop 3
	v_cvt_pk_bf16_f32 v142, v142, v143
	v_cvt_pk_bf16_f32 v143, v144, v145
	s_nop 1
	v_cvt_pk_bf16_f32 v144, v162, v163
	v_cvt_pk_bf16_f32 v145, v164, v165
	v_cndmask_b32_e64 v141, v141, v144, s[42:43]
	v_cndmask_b32_e64 v166, v166, v145, s[42:43]
	v_mfma_f32_16x16x32_bf16 v[146:149], v[60:63], v[142:145], v[146:149]
	v_mfma_f32_16x16x32_bf16 v[162:165], v[76:79], v[142:145], v[150:153]
	v_mfma_f32_16x16x32_bf16 v[228:231], v[92:95], v[142:145], v[154:157]
	v_mfma_f32_16x16x32_bf16 v[156:159], v[108:111], v[142:145], v[158:161]
	s_nop 2
	v_cndmask_b32_e64 v160, v167, v142, s[42:43]
	v_cndmask_b32_e64 v161, v190, v143, s[42:43]
	ds_read_b128 v[142:145], v204 offset:384
	ds_read_b128 v[150:153], v205 offset:192
	ds_read_b128 v[238:241], v205 offset:208
	ds_read_b128 v[208:211], v204 offset:448
	ds_read_b128 v[242:245], v205 offset:224
	ds_read_b128 v[246:249], v205 offset:240
	ds_read_b128 v[190:193], v206
	s_waitcnt lgkmcnt(0)
	v_mfma_f32_16x16x32_bf16 v[142:145], v[190:193], v[150:153], v[142:145]
	ds_read_b128 v[150:153], v207
	s_waitcnt lgkmcnt(0)
	v_mfma_f32_16x16x32_bf16 v[150:153], v[150:153], v[242:245], v[208:211]
	s_nop 2
	v_add_u32_e32 v208, 0x21e00, v140
	ds_read_b128 v[190:193], v208
	v_add_u32_e32 v209, 0x22600, v140
	s_waitcnt lgkmcnt(0)
	v_mfma_f32_16x16x32_bf16 v[142:145], v[190:193], v[238:241], v[142:145]
	ds_read_b128 v[190:193], v209
	s_waitcnt lgkmcnt(0)
	v_mfma_f32_16x16x32_bf16 v[150:153], v[190:193], v[246:249], v[150:153]
	s_nop 4
	v_cvt_pk_bf16_f32 v190, v142, v143
	v_cvt_pk_bf16_f32 v191, v144, v145
	s_nop 0
	v_cvt_pk_bf16_f32 v192, v150, v151
	v_cvt_pk_bf16_f32 v193, v152, v153
	v_cndmask_b32_e64 v219, v141, v192, s[44:45]
	v_cndmask_b32_e64 v218, v166, v193, s[44:45]
	v_mfma_f32_16x16x32_bf16 v[140:143], v[112:115], v[190:193], v[156:159]
	s_nop 2
	v_cndmask_b32_e64 v156, v161, v191, s[44:45]
	v_lshlrev_b32_e32 v215, 16, v156
	v_and_b32_e32 v216, 0xffff0000, v156
	v_lshlrev_b32_e32 v156, 2, v217
	v_add_u32_e32 v210, s6, v156
	v_mfma_f32_16x16x32_bf16 v[152:155], v[64:67], v[190:193], v[146:149]
	v_add_u32_e32 v211, s53, v156
	v_cndmask_b32_e64 v157, v160, v190, s[44:45]
	v_add_u32_e32 v212, s54, v156
	v_mfma_f32_16x16x32_bf16 v[144:147], v[80:83], v[190:193], v[162:165]
	v_lshlrev_b32_e32 v221, 16, v157
	v_and_b32_e32 v214, 0xffff0000, v157
	ds_read_b128 v[156:159], v212
	ds_read_b128 v[164:167], v210
	ds_read_b128 v[160:163], v211
	v_mfma_f32_16x16x32_bf16 v[148:151], v[96:99], v[190:193], v[228:231]
	s_waitcnt lgkmcnt(1)
	v_add_f32_e32 v152, v152, v164
	v_exp_f32_e32 v152, v152
	v_and_b32_e32 v164, 0xffff0000, v219
	s_waitcnt lgkmcnt(0)
	s_nop 2
	v_add_f32_e32 v148, v148, v160
	v_exp_f32_e32 v148, v148
	v_add_f32_e32 v152, 1.0, v152
	v_rcp_f32_e64 v152, -v152
	v_add_f32_e32 v149, v149, v161
	v_add_f32_e32 v148, 1.0, v148
	v_rcp_f32_e32 v148, v148
	v_mul_f32_e32 v152, v156, v152
	v_exp_f32_e32 v190, v152
	v_exp_f32_e32 v149, v149
	v_mul_f32_e32 v148, v148, v221
	v_or_b32_e32 v161, 16, v217
	v_fma_f32 v152, -v190, v190, 1.0
	v_max_f32_e32 v152, 0, v152
	v_sqrt_f32_e32 v152, v152
	v_add_f32_e32 v149, 1.0, v149
	v_rcp_f32_e32 v149, v149
	v_mul_f32_e32 v191, v148, v152
	v_mul_u32_u24_e32 v148, 0x210, v213
	v_add_lshl_u32 v160, v220, v148, 3
	v_add_f32_e32 v148, v153, v165
	v_exp_f32_e32 v148, v148
	v_mul_f32_e32 v149, v149, v214
	v_add_u32_e32 v213, s98, v160
	ds_write_b64 v213, v[190:191]
	v_add_f32_e32 v148, 1.0, v148
	v_rcp_f32_e64 v148, -v148
	v_lshlrev_b32_e32 v165, 16, v218
	v_mul_f32_e32 v148, v157, v148
	v_exp_f32_e32 v148, v148
	s_nop 0
	v_fma_f32 v152, -v148, v148, 1.0
	v_max_f32_e32 v152, 0, v152
	v_sqrt_f32_e32 v152, v152
	s_nop 0
	v_mul_f32_e32 v149, v149, v152
	v_add_u32_e32 v152, 0x420, v160
	v_add_u32_e32 v214, s98, v152
	ds_write_b64 v214, v[148:149]
	v_add_f32_e32 v148, v154, v166
	v_exp_f32_e32 v148, v148
	v_add_f32_e32 v149, v150, v162
	v_exp_f32_e32 v149, v149
	v_and_b32_e32 v166, 0xffff0000, v218
	v_add_f32_e32 v148, 1.0, v148
	v_rcp_f32_e64 v148, -v148
	v_add_f32_e32 v149, 1.0, v149
	v_rcp_f32_e32 v149, v149
	v_mul_f32_e32 v148, v158, v148
	v_exp_f32_e32 v148, v148
	v_mul_f32_e32 v149, v149, v215
	v_fma_f32 v150, -v148, v148, 1.0
	v_max_f32_e32 v150, 0, v150
	v_sqrt_f32_e32 v150, v150
	s_nop 0
	v_mul_f32_e32 v149, v149, v150
	v_add_u32_e32 v150, 0x840, v160
	v_add_u32_e32 v215, s98, v150
	ds_write_b64 v215, v[148:149]
	v_add_f32_e32 v148, v155, v167
	v_exp_f32_e32 v148, v148
	v_add_f32_e32 v149, v151, v163
	v_exp_f32_e32 v149, v149
	v_lshlrev_b32_e32 v163, 16, v219
	v_add_f32_e32 v148, 1.0, v148
	v_rcp_f32_e64 v148, -v148
	v_add_f32_e32 v149, 1.0, v149
	v_rcp_f32_e32 v149, v149
	v_mul_f32_e32 v148, v159, v148
	v_exp_f32_e32 v148, v148
	v_mul_f32_e32 v149, v149, v216
	v_fma_f32 v150, -v148, v148, 1.0
	v_max_f32_e32 v150, 0, v150
	v_sqrt_f32_e32 v150, v150
	s_nop 0
	v_mul_f32_e32 v149, v149, v150
	v_add_u32_e32 v150, 0xc60, v160
	v_add_u32_e32 v216, s98, v150
	ds_write_b64 v216, v[148:149]
	v_lshlrev_b32_e32 v148, 2, v161
	v_add_u32_e32 v217, s6, v148
	ds_read_b128 v[156:159], v217
	v_add_u32_e32 v218, s53, v148
	ds_read_b128 v[152:155], v218
	v_add_u32_e32 v219, s54, v148
	ds_read_b128 v[148:151], v219
	s_waitcnt lgkmcnt(2)
	v_add_f32_e32 v144, v144, v156
	v_exp_f32_e32 v144, v144
	s_waitcnt lgkmcnt(1)
	v_add_f32_e32 v140, v140, v152
	v_exp_f32_e32 v140, v140
	v_add_f32_e32 v141, v141, v153
	v_add_f32_e32 v144, 1.0, v144
	v_rcp_f32_e64 v144, -v144
	v_add_f32_e32 v140, 1.0, v140
	v_rcp_f32_e32 v140, v140
	v_exp_f32_e32 v141, v141
	s_waitcnt lgkmcnt(0)
	v_mul_f32_e32 v144, v148, v144
	v_exp_f32_e32 v162, v144
	v_mul_f32_e32 v140, v140, v163
	v_add_f32_e32 v141, 1.0, v141
	v_rcp_f32_e32 v141, v141
	v_fma_f32 v144, -v162, v162, 1.0
	v_max_f32_e32 v144, 0, v144
	v_sqrt_f32_e32 v144, v144
	v_mul_f32_e32 v141, v141, v164
	v_mul_f32_e32 v163, v140, v144
	v_mul_u32_u24_e32 v140, 0x84, v161
	v_add_lshl_u32 v140, v140, v220, 3
	v_add_u32_e32 v220, s98, v140
	v_add_f32_e32 v140, v145, v157
	v_exp_f32_e32 v140, v140
	ds_write_b64 v220, v[162:163]
	v_mov_b32_e32 v161, v1
	v_add_f32_e32 v140, 1.0, v140
	v_rcp_f32_e64 v140, -v140
	s_nop 0
	v_mul_f32_e32 v140, v149, v140
	v_exp_f32_e32 v140, v140
	s_nop 0
	v_fma_f32 v144, -v140, v140, 1.0
	v_max_f32_e32 v144, 0, v144
	v_sqrt_f32_e32 v144, v144
	s_nop 0
	v_mul_f32_e32 v141, v141, v144
	v_add_u32_e32 v144, 0x4620, v160
	v_add_u32_e32 v221, s98, v144
	ds_write_b64 v221, v[140:141]
	v_add_f32_e32 v140, v146, v158
	v_exp_f32_e32 v140, v140
	v_add_f32_e32 v141, v142, v154
	v_exp_f32_e32 v141, v141
	v_add_f32_e32 v140, 1.0, v140
	v_rcp_f32_e64 v140, -v140
	v_add_f32_e32 v141, 1.0, v141
	v_rcp_f32_e32 v141, v141
	v_mul_f32_e32 v140, v150, v140
	v_exp_f32_e32 v140, v140
	v_mul_f32_e32 v141, v141, v165
	v_fma_f32 v142, -v140, v140, 1.0
	v_max_f32_e32 v142, 0, v142
	v_sqrt_f32_e32 v142, v142
	s_nop 0
	v_mul_f32_e32 v141, v141, v142
	v_add_u32_e32 v142, 0x4a40, v160
	v_add_u32_e32 v222, s98, v142
	ds_write_b64 v222, v[140:141]
	v_add_f32_e32 v140, v147, v159
	v_exp_f32_e32 v140, v140
	v_add_f32_e32 v141, v143, v155
	v_exp_f32_e32 v141, v141
	v_add_f32_e32 v140, 1.0, v140
	v_rcp_f32_e64 v140, -v140
	v_add_f32_e32 v141, 1.0, v141
	v_rcp_f32_e32 v141, v141
	v_mul_f32_e32 v140, v151, v140
	v_exp_f32_e32 v140, v140
	v_mul_f32_e32 v141, v141, v166
	v_fma_f32 v142, -v140, v140, 1.0
	v_max_f32_e32 v142, 0, v142
	v_sqrt_f32_e32 v142, v142
	s_nop 0
	v_mul_f32_e32 v141, v141, v142
	v_add_u32_e32 v142, 0x4e60, v160
	v_add_u32_e32 v223, s98, v142
	ds_write_b64 v223, v[140:141]
	s_waitcnt lgkmcnt(0)
	s_barrier
	ds_read_b128 v[148:151], v224
	ds_read_b128 v[152:155], v224 offset:16
	ds_read_b128 v[144:147], v224 offset:32
	ds_read_b128 v[140:143], v224 offset:48
	s_waitcnt lgkmcnt(3)
	v_fma_f32 v149, 0, v148, v149
	v_fma_f32 v156, v150, v149, v151
	v_mul_f32_e32 v157, v148, v150
	s_waitcnt lgkmcnt(2)
	v_fma_f32 v158, v152, v156, v153
	v_mul_f32_e32 v159, v157, v152
	v_mul_f32_e32 v160, v154, v159
	v_fmac_f32_e32 v155, v154, v158
	s_waitcnt lgkmcnt(1)
	v_fma_f32 v145, v144, v155, v145
	v_mul_f32_e32 v144, v144, v160
	v_mul_f32_e32 v154, v146, v144
	v_fmac_f32_e32 v147, v146, v145
	s_waitcnt lgkmcnt(0)
	v_fma_f32 v141, v140, v147, v141
	v_mul_f32_e32 v140, v140, v154
	v_mul_f32_e32 v146, v142, v140
	v_fmac_f32_e32 v143, v142, v141
	v_mov_b32_e32 v142, 1.0
	v_mov_b32_e32 v150, v1
	v_mov_b32_e32 v151, 1.0
	v_mov_b32_dpp v142, v146 row_shr:1 row_mask:0xf bank_mask:0xf
	v_mov_b32_dpp v150, v143 row_shr:1 row_mask:0xf bank_mask:0xf
	v_fma_f32 v150, v146, v150, v143
	v_mul_f32_e32 v142, v146, v142
	v_mov_b32_e32 v152, v1
	s_nop 0
	v_mov_b32_dpp v151, v142 row_shr:2 row_mask:0xf bank_mask:0xf
	v_mov_b32_dpp v152, v150 row_shr:2 row_mask:0xf bank_mask:0xf
	v_fmac_f32_e32 v150, v142, v152
	v_mul_f32_e32 v142, v142, v151
	v_mov_b32_e32 v151, 1.0
	v_mov_b32_e32 v152, v1
	s_nop 0
	v_mov_b32_dpp v151, v142 row_shr:4 row_mask:0xf bank_mask:0xf
	v_mov_b32_dpp v152, v150 row_shr:4 row_mask:0xf bank_mask:0xf
	v_fmac_f32_e32 v150, v142, v152
	v_mul_f32_e32 v142, v142, v151
	v_mov_b32_e32 v151, 1.0
	v_mov_b32_e32 v152, v1
	s_nop 0
	v_mov_b32_dpp v151, v142 row_shr:8 row_mask:0xf bank_mask:0xf
	v_mov_b32_dpp v152, v150 row_shr:8 row_mask:0xf bank_mask:0xf
	v_fmac_f32_e32 v150, v142, v152
	v_mul_f32_e32 v142, v142, v151
	v_mov_b32_e32 v151, 1.0
	v_mov_b32_dpp v161, v150 row_shr:1 row_mask:0xf bank_mask:0xf
	v_fmac_f32_e32 v150, 0, v142
	v_mov_b32_dpp v151, v142 row_shr:1 row_mask:0xf bank_mask:0xf
	v_fmac_f32_e32 v161, 0, v151
	ds_bpermute_b32 v225, v196, v150
	ds_read_b128 v[150:153], v226
	v_fmac_f32_e32 v145, v144, v161
	v_fmac_f32_e32 v149, v148, v161
	v_fmac_f32_e32 v147, v154, v161
	v_fmac_f32_e32 v141, v140, v161
	s_waitcnt lgkmcnt(0)
	v_lshlrev_b32_e32 v163, 16, v152
	v_lshlrev_b32_e32 v142, 16, v150
	v_mul_f32_e32 v144, v145, v163
	v_mul_f32_e32 v145, 0xbfb8aa3b, v163
	v_mul_f32_e32 v148, v149, v142
	v_mul_f32_e32 v142, 0xbfb8aa3b, v142
	v_exp_f32_e32 v145, v145
	v_exp_f32_e32 v142, v142
	v_and_b32_e32 v150, 0xffff0000, v150
	v_and_b32_e32 v152, 0xffff0000, v152
	v_add_f32_e32 v145, 1.0, v145
	v_add_f32_e32 v142, 1.0, v142
	v_rcp_f32_e32 v145, v145
	v_rcp_f32_e32 v142, v142
	v_lshlrev_b32_e32 v164, 16, v153
	v_lshlrev_b32_e32 v162, 16, v151
	v_fmac_f32_e32 v156, v157, v161
	v_mul_f32_e32 v149, 0xbfb8aa3b, v150
	v_mul_f32_e32 v144, v144, v145
	v_mul_f32_e32 v145, v147, v152
	v_mul_f32_e32 v147, 0xbfb8aa3b, v152
	v_mul_f32_e32 v140, v141, v164
	v_mul_f32_e32 v141, 0xbfb8aa3b, v164
	v_mul_f32_e32 v142, v148, v142
	v_mul_f32_e32 v148, v156, v150
	v_exp_f32_e32 v149, v149
	v_mul_f32_e32 v150, 0xbfb8aa3b, v162
	v_exp_f32_e32 v147, v147
	v_exp_f32_e32 v141, v141
	v_exp_f32_e32 v150, v150
	v_add_f32_e32 v149, 1.0, v149
	v_add_f32_e32 v147, 1.0, v147
	v_add_f32_e32 v141, 1.0, v141
	v_rcp_f32_e32 v149, v149
	v_add_f32_e32 v150, 1.0, v150
	v_rcp_f32_e32 v147, v147
	v_rcp_f32_e32 v141, v141
	v_rcp_f32_e32 v150, v150
	v_and_b32_e32 v153, 0xffff0000, v153
	v_fmac_f32_e32 v158, v159, v161
	v_and_b32_e32 v151, 0xffff0000, v151
	v_mul_f32_e32 v148, v148, v149
	v_mul_f32_e32 v149, v158, v162
	v_fmac_f32_e32 v155, v160, v161
	v_mul_f32_e32 v145, v145, v147
	v_mul_f32_e32 v147, v140, v141
	v_mul_f32_e32 v141, 0xbfb8aa3b, v153
	v_mul_f32_e32 v149, v149, v150
	v_mul_f32_e32 v150, v155, v151
	v_mul_f32_e32 v151, 0xbfb8aa3b, v151
	v_exp_f32_e32 v141, v141
	v_exp_f32_e32 v151, v151
	v_fmac_f32_e32 v143, v146, v161
	v_mul_f32_e32 v140, v143, v153
	v_add_f32_e32 v141, 1.0, v141
	v_add_f32_e32 v151, 1.0, v151
	v_rcp_f32_e32 v141, v141
	v_rcp_f32_e32 v151, v151
	v_mul_f32_e32 v143, v140, v141
	v_mul_f32_e32 v150, v150, v151
	v_cvt_pk_bf16_f32 v140, v142, v148
	v_cvt_pk_bf16_f32 v141, v149, v150
	v_cvt_pk_bf16_f32 v142, v144, v145
	v_cvt_pk_bf16_f32 v143, v147, v143
	ds_write_b128 v227, v[140:143]
	s_waitcnt vmcnt(5)
	ds_write_b128 v177, v[124:127] offset:816
	s_waitcnt vmcnt(4)
	ds_write_b128 v179, v[128:131] offset:816
	s_waitcnt vmcnt(3)
	ds_write_b128 v181, v[132:135] offset:816
	s_waitcnt vmcnt(2)
	ds_write_b128 v199, v[136:139] offset:816
	s_and_saveexec_b64 s[10:11], s[38:39]
	ds_write_b128 v177, v[116:119]
	s_or_b64 exec, exec, s[10:11]
	s_lshl_b32 s7, s22, 3
	s_lshl_b32 s6, s23, 8
	s_and_b32 s7, s7, 0xc0
	s_or_b32 s6, s7, s6
	s_add_u32 s6, s6, s20
	s_addc_u32 s7, 0, s21
	v_and_b32_e32 v0, 3, v182
	v_lshl_add_u64 v[124:125], s[6:7], 0, v[184:185]
	v_lshlrev_b32_e32 v0, 4, v0
	v_lshl_add_u64 v[124:125], v[124:125], 0, v[0:1]
	v_mul_u32_u24_e32 v228, 0x110, v183
	v_lshl_add_u64 v[182:183], s[16:17], 0, v[124:125]
	s_movk_i32 s20, 0x100
	s_waitcnt vmcnt(0)
	v_readfirstlane_b32 s100, v172
	v_readfirstlane_b32 s101, v173
	v_and_b32_e32 v0, 15, v186
	v_lshlrev_b32_e32 v0, 4, v0
	v_subrev_u32_e32 v2, s100, v2
	v_lshl_add_u32 v2, v168, 11, v2
	v_lshl_or_b32 v174, v174, 11, v0
	v_lshl_or_b32 v176, v176, 11, v0
	v_lshl_or_b32 v178, v178, 11, v0
	v_lshl_or_b32 v180, v180, 11, v0
	v_and_b32_e32 v141, 63, v186
	v_and_b32_e32 v142, 15, v141
	v_lshrrev_b32_e32 v143, 4, v141
	v_lshrrev_b32_e32 v144, 6, v186
	v_lshl_or_b32 v145, v144, 4, v142
	v_mul_u32_u24_e32 v146, 0x880, v143
	v_lshl_add_u32 v146, v145, 1, v146
	v_add_u32_e32 v0, 0x1c800, v146
	v_add_u32_e32 v175, 0x1a600, v146
	v_readfirstlane_b32 s6, v2
	v_lshlrev_b32_e32 v147, 11, v142
	v_lshl_add_u32 v147, v143, 4, v147
	v_add_u32_e32 v2, s6, v147
	v_readfirstlane_b32 s6, v182
	v_readfirstlane_b32 s7, v183
	v_lshlrev_b32_e32 v148, 12, v142
	v_lshl_add_u32 v148, v143, 4, v148
	v_mov_b32_e32 v149, 0
	v_lshl_add_u64 v[182:183], s[6:7], 0, v[148:149]
	s_add_u32 s6, s100, 0x40000
	s_addc_u32 s7, s101, 0
	global_load_dwordx4 v[120:123], v2, s[6:7]
	s_waitcnt vmcnt(0)
	v_lshrrev_b32_e32 v141, 6, v186
	v_and_b32_e32 v142, 63, v186
	v_and_b32_e32 v143, 15, v142
	v_lshrrev_b32_e32 v144, 4, v142
	v_lshl_or_b32 v145, v141, 4, v143
	v_mul_u32_u24_e32 v146, 0x1100, v144
	v_lshlrev_b32_e32 v147, 3, v145
	v_lshrrev_b32_e32 v148, 1, v141
	v_lshlrev_b32_e32 v148, 4, v148
	v_add3_u32 v213, v146, v147, v148
	v_add_u32_e32 v213, 0x11000, v213
	v_lshl_add_u32 v149, v141, 2, v144
	v_mul_u32_u24_e32 v150, 0x440, v149
	v_lshlrev_b32_e32 v151, 6, v143
	v_lshrrev_b32_e32 v152, 2, v143
	v_lshlrev_b32_e32 v152, 4, v152
	v_add3_u32 v224, v150, v151, v152
	v_add_u32_e32 v224, 0x11000, v224
	s_add_u32 s100, s100, 0x80000
	s_addc_u32 s101, s101, 0
	s_sub_u32 s6, s100, 0x1800
	s_subb_u32 s7, s101, 0
	global_load_dwordx4 v[124:127], v174, s[100:101]
	global_load_dwordx4 v[128:131], v176, s[100:101]
	global_load_dwordx4 v[132:135], v178, s[100:101]
	global_load_dwordx4 v[136:139], v180, s[100:101]
	s_and_saveexec_b64 s[10:11], s[38:39]
	s_cbranch_execz .Lrnn_pre_halo
	global_load_dwordx4 v[116:119], v174, s[6:7]

.Lrnn_wd:
	ds_write_b16 v175, v120
	ds_write_b16_d16_hi v175, v120 offset:272
	ds_write_b16 v175, v121 offset:544
	ds_write_b16_d16_hi v175, v121 offset:816
	ds_write_b16 v175, v122 offset:1088
	ds_write_b16_d16_hi v175, v122 offset:1360
	ds_write_b16 v175, v123 offset:1632
	ds_write_b16_d16_hi v175, v123 offset:1904
	s_nop 0
	global_load_dwordx4 v[120:123], v2, s[100:101]
	global_store_dwordx4 v[182:183], v[148:151], off sc1
	v_cvt_pk_bf16_f32 v140, v140, v141
	v_cvt_pk_bf16_f32 v141, v142, v143
	v_cvt_pk_bf16_f32 v142, v160, v161
	v_cvt_pk_bf16_f32 v143, v162, v163
	v_cndmask_b32_e32 v229, 0, v140, vcc
	v_cndmask_b32_e32 v230, 0, v141, vcc
	v_mfma_f32_16x16x32_bf16 v[156:159], v[52:55], v[140:143], 0
	v_cndmask_b32_e32 v184, 0, v142, vcc
	v_cndmask_b32_e32 v185, 0, v143, vcc
	v_mfma_f32_16x16x32_bf16 v[144:147], v[68:71], v[140:143], 0
	v_mfma_f32_16x16x32_bf16 v[148:151], v[84:87], v[140:143], 0
	v_mfma_f32_16x16x32_bf16 v[152:155], v[100:103], v[140:143], 0
	s_waitcnt lgkmcnt(12)
	v_mfma_f32_16x16x32_bf16 v[200:203], v[20:23], v[190:193], v[200:203]
	s_waitcnt lgkmcnt(9)
	v_mfma_f32_16x16x32_bf16 v[164:167], v[28:31], v[242:245], v[164:167]
	v_mfma_f32_16x16x32_bf16 v[200:203], v[24:27], v[238:241], v[200:203]
	s_waitcnt lgkmcnt(0)
	v_mfma_f32_16x16x32_bf16 v[164:167], v[32:35], v[246:249], v[164:167]
	ds_read_b128 v[140:143], v204 offset:256
	ds_read_b128 v[190:193], v205 offset:128
	ds_read_b128 v[238:241], v205 offset:144
	ds_read_b128 v[160:163], v204 offset:320
	ds_read_b128 v[242:245], v205 offset:160
	ds_read_b128 v[246:249], v205 offset:176
	ds_read_b128 v[214:217], v206
	ds_read_b128 v[218:221], v207
	s_nop 1
	v_cvt_pk_bf16_f32 v200, v200, v201
	v_cvt_pk_bf16_f32 v201, v202, v203
	v_cvt_pk_bf16_f32 v202, v164, v165
	v_cvt_pk_bf16_f32 v203, v166, v167
	v_cndmask_b32_e64 v229, v229, v200, s[40:41]
	v_cndmask_b32_e64 v230, v230, v201, s[40:41]
	v_mfma_f32_16x16x32_bf16 v[156:159], v[56:59], v[200:203], v[156:159]
	v_cndmask_b32_e64 v184, v184, v202, s[40:41]
	v_cndmask_b32_e64 v185, v185, v203, s[40:41]
	v_mfma_f32_16x16x32_bf16 v[144:147], v[72:75], v[200:203], v[144:147]
	v_mfma_f32_16x16x32_bf16 v[148:151], v[88:91], v[200:203], v[148:151]
	v_mfma_f32_16x16x32_bf16 v[152:155], v[104:107], v[200:203], v[152:155]
	s_waitcnt lgkmcnt(6)
	v_mfma_f32_16x16x32_bf16 v[140:143], v[36:39], v[190:193], v[140:143]
	s_waitcnt lgkmcnt(3)
	v_mfma_f32_16x16x32_bf16 v[160:163], v[44:47], v[242:245], v[160:163]
	v_mfma_f32_16x16x32_bf16 v[140:143], v[40:43], v[238:241], v[140:143]
	s_waitcnt lgkmcnt(2)
	v_mfma_f32_16x16x32_bf16 v[160:163], v[48:51], v[246:249], v[160:163]
	ds_read_b128 v[200:203], v204 offset:384
	ds_read_b128 v[190:193], v205 offset:192
	ds_read_b128 v[238:241], v205 offset:208
	ds_read_b128 v[164:167], v204 offset:448
	ds_read_b128 v[242:245], v205 offset:224
	ds_read_b128 v[246:249], v205 offset:240
	s_nop 3
	v_cvt_pk_bf16_f32 v140, v140, v141
	v_cvt_pk_bf16_f32 v141, v142, v143
	v_cvt_pk_bf16_f32 v142, v160, v161
	v_cvt_pk_bf16_f32 v143, v162, v163
	v_cndmask_b32_e64 v229, v229, v140, s[42:43]
	v_cndmask_b32_e64 v230, v230, v141, s[42:43]
	v_mfma_f32_16x16x32_bf16 v[156:159], v[60:63], v[140:143], v[156:159]
	v_cndmask_b32_e64 v184, v184, v142, s[42:43]
	v_cndmask_b32_e64 v185, v185, v143, s[42:43]
	v_mfma_f32_16x16x32_bf16 v[144:147], v[76:79], v[140:143], v[144:147]
	v_mfma_f32_16x16x32_bf16 v[148:151], v[92:95], v[140:143], v[148:151]
	v_mfma_f32_16x16x32_bf16 v[152:155], v[108:111], v[140:143], v[152:155]
	ds_read_b128 v[140:143], v208
	ds_read_b128 v[160:163], v209
	s_waitcnt lgkmcnt(6)
	v_mfma_f32_16x16x32_bf16 v[200:203], v[214:217], v[190:193], v[200:203]
	s_waitcnt lgkmcnt(3)
	v_mfma_f32_16x16x32_bf16 v[164:167], v[218:221], v[242:245], v[164:167]
	s_waitcnt lgkmcnt(1)
	v_mfma_f32_16x16x32_bf16 v[200:203], v[140:143], v[238:241], v[200:203]
	s_waitcnt lgkmcnt(0)
	v_mfma_f32_16x16x32_bf16 v[164:167], v[160:163], v[246:249], v[164:167]
	ds_read_b128 v[190:193], v210
	ds_read_b128 v[238:241], v210 offset:128
	ds_read_b128 v[242:245], v210 offset:256
	ds_read_b128 v[246:249], v210 offset:64
	ds_read_b128 v[214:217], v210 offset:192
	ds_read_b128 v[218:221], v210 offset:320
	s_nop 3
	v_cvt_pk_bf16_f32 v200, v200, v201
	v_cvt_pk_bf16_f32 v201, v202, v203
	v_cvt_pk_bf16_f32 v202, v164, v165
	v_cvt_pk_bf16_f32 v203, v166, v167
	v_cndmask_b32_e64 v229, v229, v200, s[44:45]
	v_cndmask_b32_e64 v230, v230, v201, s[44:45]
	v_mfma_f32_16x16x32_bf16 v[156:159], v[64:67], v[200:203], v[156:159]
	v_cndmask_b32_e64 v184, v184, v202, s[44:45]
	v_cndmask_b32_e64 v185, v185, v203, s[44:45]
	v_mfma_f32_16x16x32_bf16 v[144:147], v[80:83], v[200:203], v[144:147]
	v_mfma_f32_16x16x32_bf16 v[148:151], v[96:99], v[200:203], v[148:151]
	v_mfma_f32_16x16x32_bf16 v[152:155], v[112:115], v[200:203], v[152:155]
	v_lshlrev_b32_e32 v231, 16, v229
	v_and_b32_e32 v229, 0xffff0000, v229
	v_lshlrev_b32_e32 v232, 16, v230
	v_and_b32_e32 v230, 0xffff0000, v230
	v_lshlrev_b32_e32 v172, 16, v184
	v_and_b32_e32 v184, 0xffff0000, v184
	v_lshlrev_b32_e32 v3, 16, v185
	v_and_b32_e32 v185, 0xffff0000, v185
	s_nop 1
	s_waitcnt lgkmcnt(5)
	v_add_f32_e32 v156, v156, v190
	v_add_f32_e32 v157, v157, v191
	v_add_f32_e32 v158, v158, v192
	v_add_f32_e32 v159, v159, v193
	s_waitcnt lgkmcnt(4)
	v_add_f32_e32 v148, v148, v238
	v_add_f32_e32 v149, v149, v239
	v_add_f32_e32 v150, v150, v240
	v_add_f32_e32 v151, v151, v241
	v_exp_f32_e32 v156, v156
	v_exp_f32_e32 v157, v157
	v_exp_f32_e32 v158, v158
	v_exp_f32_e32 v159, v159
	v_exp_f32_e32 v148, v148
	v_exp_f32_e32 v149, v149
	v_exp_f32_e32 v150, v150
	v_exp_f32_e32 v151, v151
	s_waitcnt lgkmcnt(2)
	v_add_f32_e32 v144, v144, v246
	v_add_f32_e32 v145, v145, v247
	v_add_f32_e32 v146, v146, v248
	v_add_f32_e32 v147, v147, v249
	s_waitcnt lgkmcnt(1)
	v_add_f32_e32 v152, v152, v214
	v_add_f32_e32 v153, v153, v215
	v_add_f32_e32 v154, v154, v216
	v_add_f32_e32 v155, v155, v217
	v_exp_f32_e32 v144, v144
	v_exp_f32_e32 v145, v145
	v_exp_f32_e32 v146, v146
	v_exp_f32_e32 v147, v147
	v_exp_f32_e32 v152, v152
	v_exp_f32_e32 v153, v153
	v_exp_f32_e32 v154, v154
	v_exp_f32_e32 v155, v155
	v_add_f32_e32 v156, 1.0, v156
	v_add_f32_e32 v157, 1.0, v157
	v_add_f32_e32 v158, 1.0, v158
	v_add_f32_e32 v159, 1.0, v159
	v_add_f32_e32 v144, 1.0, v144
	v_add_f32_e32 v145, 1.0, v145
	v_add_f32_e32 v146, 1.0, v146
	v_add_f32_e32 v147, 1.0, v147
	v_add_f32_e32 v148, 1.0, v148
	v_add_f32_e32 v149, 1.0, v149
	v_add_f32_e32 v150, 1.0, v150
	v_add_f32_e32 v151, 1.0, v151
	v_add_f32_e32 v152, 1.0, v152
	v_add_f32_e32 v153, 1.0, v153
	v_add_f32_e32 v154, 1.0, v154
	v_add_f32_e32 v155, 1.0, v155
	v_rcp_f32_e64 v156, -v156
	v_rcp_f32_e64 v157, -v157
	v_rcp_f32_e64 v158, -v158
	v_rcp_f32_e64 v159, -v159
	v_rcp_f32_e64 v144, -v144
	v_rcp_f32_e64 v145, -v145
	v_rcp_f32_e64 v146, -v146
	v_rcp_f32_e64 v147, -v147
	v_rcp_f32_e32 v148, v148
	v_rcp_f32_e32 v149, v149
	v_rcp_f32_e32 v150, v150
	v_rcp_f32_e32 v151, v151
	v_rcp_f32_e32 v152, v152
	v_rcp_f32_e32 v153, v153
	v_rcp_f32_e32 v154, v154
	v_rcp_f32_e32 v155, v155
	s_waitcnt lgkmcnt(0)
	v_mul_f32_e32 v156, v242, v156
	v_mul_f32_e32 v157, v243, v157
	v_mul_f32_e32 v158, v244, v158
	v_mul_f32_e32 v159, v245, v159
	v_mul_f32_e32 v144, v218, v144
	v_mul_f32_e32 v145, v219, v145
	v_mul_f32_e32 v146, v220, v146
	v_mul_f32_e32 v147, v221, v147
	v_mul_f32_e32 v148, v148, v231
	v_mul_f32_e32 v149, v149, v229
	v_mul_f32_e32 v150, v150, v232
	v_mul_f32_e32 v151, v151, v230
	v_mul_f32_e32 v152, v152, v172
	v_mul_f32_e32 v153, v153, v184
	v_mul_f32_e32 v154, v154, v3
	v_mul_f32_e32 v155, v155, v185
	v_exp_f32_e32 v238, v156
	v_exp_f32_e32 v240, v157
	v_exp_f32_e32 v242, v158
	v_exp_f32_e32 v244, v159
	v_exp_f32_e32 v214, v144
	v_exp_f32_e32 v216, v145
	v_exp_f32_e32 v218, v146
	v_exp_f32_e32 v220, v147
	v_fma_f32 v190, -v238, v238, 1.0
	v_fma_f32 v191, -v240, v240, 1.0
	v_fma_f32 v192, -v242, v242, 1.0
	v_fma_f32 v193, -v244, v244, 1.0
	v_fma_f32 v246, -v214, v214, 1.0
	v_fma_f32 v247, -v216, v216, 1.0
	v_fma_f32 v248, -v218, v218, 1.0
	v_fma_f32 v249, -v220, v220, 1.0
	v_max_f32_e32 v190, 0, v190
	v_max_f32_e32 v191, 0, v191
	v_max_f32_e32 v192, 0, v192
	v_max_f32_e32 v193, 0, v193
	v_max_f32_e32 v246, 0, v246
	v_max_f32_e32 v247, 0, v247
	v_max_f32_e32 v248, 0, v248
	v_max_f32_e32 v249, 0, v249
	v_sqrt_f32_e32 v190, v190
	v_sqrt_f32_e32 v191, v191
	v_sqrt_f32_e32 v192, v192
	v_sqrt_f32_e32 v193, v193
	v_sqrt_f32_e32 v246, v246
	v_sqrt_f32_e32 v247, v247
	v_sqrt_f32_e32 v248, v248
	v_sqrt_f32_e32 v249, v249
	v_mul_f32_e32 v239, v148, v190
	v_mul_f32_e32 v241, v149, v191
	v_mul_f32_e32 v243, v150, v192
	v_mul_f32_e32 v245, v151, v193
	v_mul_f32_e32 v215, v152, v246
	v_mul_f32_e32 v217, v153, v247
	v_mul_f32_e32 v219, v154, v248
	v_mul_f32_e32 v221, v155, v249
	ds_write_b64 v213, v[238:239]
	ds_write_b64 v213, v[240:241] offset:1088
	ds_write_b64 v213, v[242:243] offset:2176
	ds_write_b64 v213, v[244:245] offset:3264
	ds_write_b64 v213, v[214:215] offset:17408
	ds_write_b64 v213, v[216:217] offset:18496
	ds_write_b64 v213, v[218:219] offset:19584
	ds_write_b64 v213, v[220:221] offset:20672
	v_mov_b32_e32 v161, 0
	s_waitcnt lgkmcnt(0)
	s_barrier
	ds_read_b128 v[148:151], v224
	ds_read_b128 v[152:155], v224 offset:16
	ds_read_b128 v[144:147], v224 offset:32
	ds_read_b128 v[140:143], v224 offset:48
	s_waitcnt vmcnt(2)
	ds_write_b128 v177, v[124:127] offset:816
	ds_write_b128 v179, v[128:131] offset:816
	ds_write_b128 v181, v[132:135] offset:816
	ds_write_b128 v199, v[136:139] offset:816
	s_and_saveexec_b64 s[10:11], s[38:39]
	s_cbranch_execz .Lrnn_halo_done
	ds_write_b128 v177, v[116:119]
